# phase13 tile prologue: six first-stage loads issued together
# baseline (speedup 1.0000x reference)
; template <class ARowF>
; __device__ __forceinline__ void gemm_mainloop(f32x4 (&acc)[4][4], ARowF arow, int a_kstep, const u16* bt, int ldb, int nk, u16* sm) {
;     ...
;   const u16* pa[4]; const u16* pb[2];
; #pragma unroll
;   for (int i = 0; i < 4; ++i) pa[i] = arow(lr + 64 * i) + lc * 8;
; #pragma unroll
;   for (int i = 0; i < 2; ++i) pb[i] = bt + (size_t)(lr + 64 * i) * ldb + lc * 8;
;   u16* sA = sm; u16* sB = sm + 2 * 256 * LDSP;
;   uint4 ra[4], rb[2];
; #pragma unroll
;   for (int i = 0; i < 4; ++i) ra[i] = *(const uint4*)pa[i];
; #pragma unroll
;   for (int i = 0; i < 2; ++i) rb[i] = *(const uint4*)pb[i];
; #pragma unroll
;   for (int i = 0; i < 4; ++i) *(uint4*)(sA + (lr + 64 * i) * LDSP + lc * 8) = ra[i];
; #pragma unroll
;   for (int i = 0; i < 2; ++i) *(uint4*)(sB + (lr + 64 * i) * LDSP + lc * 8) = rb[i];
;   __syncthreads();
; __device__ __forceinline__ void phase_compress(const Params& p, u16* sm) {
;     ...
;     gemm_mainloop(acc, [&](int r) {
;       int row = m0 + r; int g = row & 1; int bc = row >> 1; int c = bc & 255; int b = bc >> 8;
;       if (c > 254) c = 254;
;       return cb + ((size_t)b * SEQ + c * 16) * 256 + g * 64;
;     }, 256, w1t, 2048, 32, sm);
.LBB0_895:
	s_lshl_b32 s4, s1, 12
	s_and_b32 s4, s4, 0x100000
	v_bitop3_b32 v22, s4, v243, v210 bitop3:0xc8
	s_lshl_b32 s4, s58, 7
	s_and_b32 s20, s58, 1
	s_and_b32 s59, s4, 0xffffff00
	s_bitcmp1_b32 s58, 0
	s_cselect_b64 s[4:5], -1, 0
	s_cmp_eq_u32 s20, 0
	s_cselect_b64 s[6:7], -1, 0
	v_or_b32_e32 v14, s59, v230
	s_and_b64 s[8:9], s[6:7], exec
	v_add_u32_e32 v2, 64, v14
	s_cselect_b32 s9, s83, s15
	s_cselect_b32 s8, s82, s14
	s_lshl_b32 s26, s20, 8
	v_readlane_b32 s34, v253, 42
	v_bfe_u32 v4, v2, 1, 8
	v_ashrrev_i32_e32 v2, 9, v2
	v_readlane_b32 s35, v253, 43
	s_add_u32 s34, s34, s26
	v_ashrrev_i32_e32 v3, 31, v2
	v_lshlrev_b32_e32 v5, 12, v4
	v_cmp_ne_u32_e32 vcc, s29, v4
	s_addc_u32 s35, s35, 0
	v_mov_b32_e32 v7, v195
	v_cndmask_b32_e32 v6, v244, v5, vcc
	v_lshlrev_b64 v[4:5], 21, v[2:3]
	v_lshl_add_u64 v[2:3], s[34:35], 0, v[4:5]
	v_lshlrev_b32_e32 v6, 1, v6
	v_lshl_add_u64 v[2:3], v[2:3], 0, v[6:7]
	v_lshl_add_u64 v[2:3], v[2:3], 0, v[212:213]
	s_ashr_i32 s26, s58, 2
	v_lshl_add_u64 v[8:9], v[2:3], 0, v[214:215]
	v_lshrrev_b32_e32 v2, 1, v14
	s_ashr_i32 s27, s26, 31
	v_and_b32_e32 v2, 0xbf, v2
	s_lshl_b64 s[26:27], s[26:27], 21
	v_lshl_or_b32 v3, v2, 12, v245
	v_cmp_ne_u32_e32 vcc, s30, v2
	s_add_u32 s36, s34, s26
	s_addc_u32 s37, s35, s27
	v_cndmask_b32_e32 v2, v244, v3, vcc
	v_lshlrev_b32_e32 v10, 1, v2
	v_mov_b32_e32 v11, v195
	v_lshl_add_u64 v[2:3], s[36:37], 0, v[10:11]
	v_lshl_add_u64 v[2:3], v[2:3], 0, v[212:213]
	v_lshl_add_u64 v[12:13], v[2:3], 0, v[214:215]
	v_add_u32_e32 v2, 0xc0, v14
	v_bfe_u32 v7, v2, 1, 8
	v_ashrrev_i32_e32 v2, 9, v2
	v_cndmask_b32_e64 v0, 0, 1, s[16:17]
	v_ashrrev_i32_e32 v3, 31, v2
	v_lshlrev_b32_e32 v11, 12, v7
	v_cmp_ne_u32_e32 vcc, s29, v7
	v_lshlrev_b32_e32 v23, 8, v0
	v_lshlrev_b32_e32 v0, 12, v14
	v_cndmask_b32_e32 v7, v244, v11, vcc
	v_lshlrev_b64 v[14:15], 21, v[2:3]
	v_and_b32_e32 v0, 0x17e000, v0
	v_mov_b32_e32 v1, v195
	v_lshl_add_u64 v[2:3], s[34:35], 0, v[14:15]
	v_lshlrev_b32_e32 v16, 1, v7
	v_mov_b32_e32 v17, v195
	v_lshl_add_u64 v[0:1], s[36:37], 0, v[0:1]
	v_lshl_add_u64 v[2:3], v[2:3], 0, v[16:17]
	v_lshl_add_u64 v[0:1], v[0:1], 0, v[212:213]
	v_lshl_add_u64 v[2:3], v[2:3], 0, v[212:213]
	v_lshl_add_u64 v[0:1], v[0:1], 0, v[214:215]
	v_lshl_add_u64 v[18:19], v[2:3], 0, v[214:215]
	v_lshl_add_u64 v[2:3], s[8:9], 0, v[214:215]
	v_lshl_add_u64 v[20:21], v[2:3], 0, v[210:211]
	global_load_dwordx4 v[0:3], v[0:1], off
	global_load_dwordx4 v[150:153], v[8:9], off
	global_load_dwordx4 v[154:157], v[12:13], off
	global_load_dwordx4 v[158:161], v[18:19], off
	global_load_dwordx4 v[162:165], v[20:21], off
	v_mov_b32_e32 v172, s31
	v_mov_b32_e32 v173, 0
	v_lshl_add_u64 v[170:171], v[20:21], 0, v[172:173]
	global_load_dwordx4 v[166:169], v[170:171], off
	v_or3_b32 v4, v4, v23, v6
	v_or3_b32 v14, v14, v23, v16
	v_lshl_add_u64 v[64:65], s[8:9], 0, v[206:207]
	v_lshl_add_u64 v[68:69], v[208:209], 0, v[4:5]
	v_lshl_add_u64 v[72:73], v[208:209], 0, v[14:15]
	s_mov_b32 s8, 0
	v_mov_b32_e32 v52, 0
	v_mov_b32_e32 v53, v195
	v_mov_b32_e32 v54, v195
	v_mov_b32_e32 v55, v195
	v_mov_b32_e32 v60, 0
	v_mov_b32_e32 v61, v195
	v_mov_b32_e32 v62, v195
	v_mov_b32_e32 v63, v195
	v_mov_b32_e32 v48, 0
	v_mov_b32_e32 v49, v195
	v_mov_b32_e32 v50, v195
	v_mov_b32_e32 v51, v195
	v_mov_b32_e32 v56, 0
	v_mov_b32_e32 v57, v195
	v_mov_b32_e32 v58, v195
	v_mov_b32_e32 v59, v195
	v_mov_b32_e32 v14, v195
	v_mov_b32_e32 v15, v195
	v_mov_b32_e32 v24, 0
	v_mov_b32_e32 v25, v195
	v_mov_b32_e32 v26, v195
	v_mov_b32_e32 v27, v195
	v_mov_b32_e32 v16, 0
	v_mov_b32_e32 v4, 0
	v_mov_b32_e32 v5, v195
	v_mov_b32_e32 v6, v195
	v_mov_b32_e32 v7, v195
	v_mov_b32_e32 v11, v195
	s_waitcnt vmcnt(0)
	v_mov_b32_e32 v28, 0
	v_mov_b32_e32 v29, v195
	v_mov_b32_e32 v30, v195
	v_mov_b32_e32 v31, v195
	v_mov_b32_e32 v32, 0
	v_mov_b32_e32 v33, v195
	v_mov_b32_e32 v34, v195
	v_mov_b32_e32 v35, v195
	v_mov_b32_e32 v36, 0
	v_mov_b32_e32 v37, v195
	v_mov_b32_e32 v38, v195
	v_mov_b32_e32 v39, v195
	v_mov_b32_e32 v40, 0
	v_mov_b32_e32 v41, v195
	v_mov_b32_e32 v42, v195
	v_mov_b32_e32 v43, v195
	v_mov_b32_e32 v44, 0
	v_mov_b32_e32 v45, v195
	v_mov_b32_e32 v46, v195
	v_mov_b32_e32 v47, v195
	ds_write_b128 v231, v[0:3]
	v_mov_b32_e32 v8, 0
	v_mov_b32_e32 v9, v195
	ds_write_b128 v232, v[150:153]
	v_mov_b32_e32 v12, 0
	v_mov_b32_e32 v13, v195
	ds_write_b128 v233, v[154:157]
	v_mov_b32_e32 v18, v195
	v_mov_b32_e32 v19, v195
	ds_write_b128 v234, v[158:161]
	ds_write_b128 v235, v[162:165]
	v_mov_b32_e32 v20, 0
	v_mov_b32_e32 v21, v195
	ds_write_b128 v236, v[166:169]
	v_or_b32_e32 v2, s26, v23
	v_or_b32_e32 v0, v2, v22
	v_mov_b32_e32 v1, s27
	v_lshl_add_u64 v[66:67], v[208:209], 0, v[0:1]
	v_or_b32_e32 v0, v2, v10
	v_lshl_add_u64 v[70:71], v[208:209], 0, v[0:1]
	v_mov_b32_e32 v22, v195
	v_mov_b32_e32 v23, v195
	v_mov_b32_e32 v0, 0
	v_mov_b32_e32 v1, v195
	v_mov_b32_e32 v2, v195
	v_mov_b32_e32 v3, v195
	v_mov_b32_e32 v10, v195
	s_waitcnt lgkmcnt(0)
	s_barrier
